# v102 mirrored: static s_setprio 1 for waves 0-3 (instead of 4-7) inside the MLA fast path
# speedup vs baseline: 1.0032x; 1.0032x over previous
.Lmla_fast:
	s_mov_b32 s42, s30
	s_cmp_ge_u32 s5, 0x1000
	s_cbranch_scc1 .Lmla_fast_prio
	s_setprio 1
